# attention item preamble: LDS-reuse barrier moved down to the first LDS write so the first-tile loads issue before the block sync
# speedup vs baseline: 1.0028x; 1.0012x over previous
; DEV void attn_item(const Params& p, int item, char* smem) {
;     ...
;   const int ntile = nkeys >> 5;
;   __syncthreads();
;   rk0 = *(const u32x4*)(Kb + (size_t)k0row * 96 + k0cc * 8);
;   rk1 = *(const u32x4*)(Kb + (size_t)k1row * 96 + k1cc * 8);
;   rv0 = *(const u32x4*)(Vb + (size_t)vrow * 8448 + vcc * 8);
;   *(u32x4*)(Ks + k0row * ASTR + k0cc * 8) = rk0;
;   if (has_k1) *(u32x4*)(Ks + k1row * ASTR + k1cc * 8) = rk1;
;   *(uint2*)(Vs + vrow * VSTR + vcc * 8) = make_uint2(rv0[0], rv0[1]);
;   *(uint2*)(Vs + vrow * VSTR + vcc * 8 + 4) = make_uint2(rv0[2], rv0[3]);
.LBB0_749:
	v_bfe_u32 v10, v172, 5, 1
	v_lshlrev_b32_e32 v0, 4, v10
	s_mul_i32 s8, s11, 0x18c000
	s_mul_hi_u32 s9, s10, 0x18c000
	v_and_b32_e32 v4, 0xffffffdf, v172
	v_lshl_add_u64 v[2:3], s[14:15], 0, v[0:1]
	s_movk_i32 s37, 0xc0
	s_add_i32 s9, s9, s8
	s_mul_i32 s8, s10, 0x18c000
	v_mad_i64_i32 v[4:5], s[14:15], v4, s37, v[2:3]
	s_add_u32 s12, s20, s8
	s_mul_i32 s11, s11, 0x108000
	s_mul_hi_u32 s34, s10, 0x108000
	global_load_dwordx4 v[156:159], v[4:5], off
	global_load_dwordx4 v[152:155], v[4:5], off offset:32
	global_load_dwordx4 v[148:151], v[4:5], off offset:64
	global_load_dwordx4 v[144:147], v[4:5], off offset:96
	global_load_dwordx4 v[140:143], v[4:5], off offset:128
	global_load_dwordx4 v[136:139], v[4:5], off offset:160
	v_or_b32_e32 v4, 32, v172
	s_addc_u32 s13, s21, s9
	s_add_i32 s11, s34, s11
	v_mad_i64_i32 v[2:3], s[14:15], v4, s37, v[2:3]
	s_mov_b32 s34, 0x2aaaaaab
	global_load_dwordx4 v[132:135], v[2:3], off
	global_load_dwordx4 v[128:131], v[2:3], off offset:32
	global_load_dwordx4 v[112:115], v[2:3], off offset:64
	global_load_dwordx4 v[116:119], v[2:3], off offset:96
	global_load_dwordx4 v[120:123], v[2:3], off offset:128
	global_load_dwordx4 v[124:127], v[2:3], off offset:160
	v_mul_hi_i32 v2, v172, s34
	v_lshrrev_b32_e32 v3, 31, v2
	v_ashrrev_i32_e32 v2, 1, v2
	v_add_u32_e32 v11, v2, v3
	v_mad_u64_u32 v[20:21], s[34:35], v11, -12, v[172:173]
	s_mul_i32 s10, s10, 0x108000
	v_mov_b64_e32 v[2:3], s[12:13]
	v_lshlrev_b32_e32 v176, 3, v20
	s_add_u32 s14, s22, s10
	v_mad_i64_i32 v[2:3], s[34:35], v11, s37, v[2:3]
	v_ashrrev_i32_e32 v177, 31, v176
	s_addc_u32 s15, s23, s11
	v_lshl_add_u64 v[2:3], v[176:177], 1, v[2:3]
	v_lshlrev_b32_e32 v4, 3, v172
	v_ashrrev_i32_e32 v12, 2, v172
	global_load_dwordx4 v[16:19], v[2:3], off
	v_mov_b64_e32 v[2:3], s[14:15]
	s_movk_i32 s14, 0x4200
	s_waitcnt vmcnt(35)
	v_and_b32_e32 v14, 24, v4
	v_mad_i64_i32 v[2:3], s[14:15], v12, s14, v[2:3]
	v_lshlrev_b32_e32 v4, 1, v14
	v_mov_b32_e32 v5, v1
	v_lshl_add_u64 v[6:7], v[2:3], 0, v[4:5]
	global_load_dwordx4 v[2:5], v[6:7], off
	v_and_b32_e32 v8, 0x7f, v172
	v_or_b32_e32 v13, 0x100, v8
	s_movk_i32 s14, 0x80
	v_mul_u32_u24_e32 v15, 0x1556, v13
	v_cmp_gt_i32_e64 s[38:39], s14, v172
	s_movk_i32 s14, 0x60
	v_mul_i32_i24_sdwa v21, v15, v226 dst_sel:DWORD dst_unused:UNUSED_PAD src0_sel:WORD_1 src1_sel:DWORD
	v_mul_u32_u24_sdwa v8, v15, s14 dst_sel:DWORD dst_unused:UNUSED_PAD src0_sel:WORD_1 src1_sel:DWORD
	s_movk_i32 s14, 0x68
	v_lshlrev_b32_e32 v8, 1, v8
	v_mov_b32_e32 v9, v1
	v_add_lshl_u32 v174, v21, v13, 3
	v_mul_lo_u32 v191, v11, s14
	v_lshlrev_b32_e32 v20, 4, v20
	s_movk_i32 s14, 0xd0
	v_lshl_add_u64 v[8:9], s[12:13], 0, v[8:9]
	v_ashrrev_i32_e32 v175, 31, v174
	v_lshl_add_u32 v20, v191, 1, v20
	v_mul_u32_u24_sdwa v188, v15, s14 dst_sel:DWORD dst_unused:UNUSED_PAD src0_sel:WORD_1 src1_sel:DWORD
	s_and_saveexec_b64 s[14:15], s[38:39]
	v_lshl_add_u64 v[168:169], v[174:175], 1, v[8:9]
	global_load_dwordx4 v[168:171], v[168:169], off
	s_or_b64 exec, exec, s[14:15]
	s_waitcnt lgkmcnt(0)
	s_barrier
	s_waitcnt vmcnt(2)
	ds_write_b128 v20, v[16:19]
	s_and_saveexec_b64 s[14:15], s[38:39]
	s_cbranch_execz .LBB0_751
	v_lshl_add_u32 v15, v174, 1, v188
	s_waitcnt vmcnt(0)
	ds_write_b128 v15, v[168:171]
